# V pass: bf16 residual operands (h0, mix) staged through LDS by LDS-DMA, 2 loads per 4 steps instead of 2 per step
# speedup vs baseline: 1.0557x; 1.0104x over previous
.LBB0_931:
	s_lshl_b32 s0, s59, 9
	s_lshl_b32 s1, s34, 9
	v_add_u32_e32 v10, s0, v191
	v_add_u32_e32 v12, s1, v191
	v_add_u32_e32 v32, s0, v190
	v_add_u32_e32 v33, s1, v190
	ds_read_b64 v[10:11], v10
	ds_read_b64 v[12:13], v12
	ds_read_b64 v[16:17], v32
	ds_read_b64 v[18:19], v33
	v_or_b32_e32 v2, s34, v1
	v_or_b32_e32 v4, s59, v0
	v_ashrrev_i32_e32 v5, 31, v4
	v_ashrrev_i32_e32 v3, 31, v2
	v_lshlrev_b64 v[2:3], 9, v[2:3]
	v_lshlrev_b64 v[14:15], 9, v[4:5]
	v_lshl_add_u64 v[4:5], v[4:5], 2, s[24:25]
	v_lshl_add_u64 v[14:15], v[146:147], 0, v[14:15]
	v_lshl_add_u64 v[2:3], v[146:147], 0, v[2:3]
	s_waitcnt lgkmcnt(0)
	v_cvt_f32_i32_e32 v21, v18
	v_cvt_f32_i32_e32 v20, v16
	v_ashrrev_i32_e32 v23, 31, v12
	v_mov_b32_e32 v22, v12
	v_ashrrev_i32_e32 v25, 31, v10
	v_mov_b32_e32 v24, v10
	v_cvt_f32_i32_e32 v18, v17
	v_ashrrev_i32_e32 v17, 31, v13
	v_mov_b32_e32 v16, v13
	v_ashrrev_i32_e32 v13, 31, v11
	v_mov_b32_e32 v12, v11
	global_load_dwordx2 v[4:5], v[4:5], off
	s_nop 0
	global_load_dwordx2 v[14:15], v[14:15], off
	s_nop 0
	global_load_dwordx2 v[2:3], v[2:3], off
	v_lshlrev_b64 v[10:11], 2, v[24:25]
	v_lshlrev_b64 v[22:23], 2, v[22:23]
	v_lshlrev_b64 v[12:13], 2, v[12:13]
	v_lshlrev_b64 v[16:17], 2, v[16:17]
	v_lshl_add_u64 v[24:25], s[20:21], 0, v[10:11]
	v_lshl_add_u64 v[26:27], s[20:21], 0, v[22:23]
	v_lshl_add_u64 v[28:29], s[20:21], 0, v[12:13]
	v_lshl_add_u64 v[10:11], s[22:23], 0, v[10:11]
	v_lshl_add_u64 v[12:13], s[22:23], 0, v[12:13]
	v_lshl_add_u64 v[30:31], s[20:21], 0, v[16:17]
	v_lshl_add_u64 v[22:23], s[22:23], 0, v[22:23]
	v_lshl_add_u64 v[16:17], s[22:23], 0, v[16:17]
	global_load_dword v24, v[24:25], off
	s_nop 0
	global_load_dword v25, v[26:27], off
	s_nop 0
	global_load_dword v26, v[28:29], off
	global_load_dword v27, v[30:31], off
	s_nop 0
	global_load_dword v10, v[10:11], off
	s_nop 0
	global_load_dword v11, v[22:23], off
	s_nop 0
	global_load_dword v12, v[12:13], off
	s_nop 0
	global_load_dword v13, v[16:17], off
	v_cvt_f32_i32_e32 v19, v19
	v_mov_b64_e32 v[6:7], s[44:45]
	v_mov_b64_e32 v[8:9], s[62:63]
	s_add_i32 s59, s59, 2
	s_add_i32 s61, s61, -2
	s_add_i32 s34, s34, 2
	s_cmp_lg_u32 s61, 0
	s_waitcnt vmcnt(9)
	v_mov_b32_e32 v16, v14
	s_waitcnt vmcnt(8)
	v_mov_b32_e32 v17, v2
	v_mov_b32_e32 v2, v15
	s_waitcnt vmcnt(6)
	v_pk_mul_f32 v[14:15], v[4:5], v[24:25]
	s_waitcnt vmcnt(4)
	v_pk_mul_f32 v[4:5], v[4:5], v[26:27]
	s_nop 0
	v_pk_mul_f32 v[4:5], v[4:5], v[18:19]
	s_waitcnt vmcnt(2)
	v_pk_mul_f32 v[10:11], v[16:17], v[10:11]
	s_waitcnt vmcnt(0)
	v_pk_mul_f32 v[2:3], v[2:3], v[12:13]
	v_pk_mul_f32 v[12:13], v[14:15], v[20:21]
	v_pk_mul_f32 v[10:11], v[10:11], 0.5 op_sel_hi:[1,0]
	v_pk_mul_f32 v[2:3], v[2:3], 0.5 op_sel_hi:[1,0]
	v_pk_mul_f32 v[10:11], v[12:13], v[10:11]
	v_pk_mul_f32 v[12:13], v[12:13], s[40:41] op_sel_hi:[1,0]
	v_pk_mul_f32 v[2:3], v[4:5], v[2:3]
	v_pk_mul_f32 v[4:5], v[4:5], s[40:41] op_sel_hi:[1,0]
	v_and_b32_e32 v15, 0x7fffffff, v13
	v_and_b32_e32 v14, 0x7fffffff, v12
	v_pk_mul_f32 v[16:17], v[12:13], v[12:13]
	v_and_b32_e32 v19, 0x7fffffff, v5
	v_and_b32_e32 v18, 0x7fffffff, v4
	v_pk_mul_f32 v[20:21], v[4:5], v[4:5]
	v_pk_fma_f32 v[22:23], v[14:15], s[50:51], v[6:7] op_sel_hi:[1,0,0]
	v_pk_fma_f32 v[24:25], v[16:17], s[64:65], v[8:9] op_sel_hi:[1,0,0]
	v_pk_fma_f32 v[6:7], v[18:19], s[50:51], v[6:7] op_sel_hi:[1,0,0]
	v_pk_fma_f32 v[8:9], v[20:21], s[64:65], v[8:9] op_sel_hi:[1,0,0]
	v_pk_fma_f32 v[22:23], v[14:15], v[22:23], s[52:53] op_sel_hi:[1,1,0]
	v_pk_fma_f32 v[24:25], v[16:17], v[24:25], s[66:67] op_sel_hi:[1,1,0]
	v_pk_fma_f32 v[6:7], v[18:19], v[6:7], s[52:53] op_sel_hi:[1,1,0]
	v_pk_fma_f32 v[8:9], v[20:21], v[8:9], s[66:67] op_sel_hi:[1,1,0]
	v_pk_fma_f32 v[22:23], v[14:15], v[22:23], s[54:55] op_sel_hi:[1,1,0]
	v_pk_fma_f32 v[24:25], v[16:17], v[24:25], s[68:69] op_sel_hi:[1,1,0]
	v_pk_fma_f32 v[6:7], v[18:19], v[6:7], s[54:55] op_sel_hi:[1,1,0]
	v_pk_fma_f32 v[8:9], v[20:21], v[8:9], s[68:69] op_sel_hi:[1,1,0]
	v_pk_fma_f32 v[22:23], v[14:15], v[22:23], s[56:57] op_sel_hi:[1,1,0]
	v_pk_fma_f32 v[24:25], v[16:17], v[24:25], s[70:71] op_sel_hi:[1,1,0]
	v_pk_fma_f32 v[6:7], v[18:19], v[6:7], s[56:57] op_sel_hi:[1,1,0]
	v_pk_fma_f32 v[8:9], v[20:21], v[8:9], s[70:71] op_sel_hi:[1,1,0]
	v_pk_fma_f32 v[22:23], v[14:15], v[22:23], s[58:59] op_sel_hi:[1,1,0]
	v_pk_fma_f32 v[16:17], v[16:17], v[24:25], s[72:73] op_sel_hi:[1,1,0]
	v_pk_fma_f32 v[6:7], v[18:19], v[6:7], s[58:59] op_sel_hi:[1,1,0]
	v_pk_fma_f32 v[8:9], v[20:21], v[8:9], s[72:73] op_sel_hi:[1,1,0]
	v_pk_fma_f32 v[20:21], v[14:15], v[22:23], s[60:61] op_sel_hi:[1,1,0]
	v_pk_fma_f32 v[16:17], v[14:15], v[16:17], v[14:15]
	v_pk_fma_f32 v[6:7], v[18:19], v[6:7], s[60:61] op_sel_hi:[1,1,0]
	v_pk_fma_f32 v[14:15], v[14:15], v[20:21], v[14:15]
	v_pk_fma_f32 v[8:9], v[18:19], v[8:9], v[18:19]
	v_pk_fma_f32 v[6:7], v[18:19], v[6:7], v[18:19]
	v_mul_f32_e32 v18, 0xbfb8aa3b, v15
	v_mul_f32_e32 v19, 0xbfb8aa3b, v14
	v_mul_f32_e32 v20, 0xbfb8aa3b, v7
	v_mul_f32_e32 v21, 0xbfb8aa3b, v6
	v_fma_f32 v22, v15, s45, -v18
	v_rndne_f32_e32 v23, v18
	v_fma_f32 v24, v14, s45, -v19
	v_rndne_f32_e32 v25, v19
	v_fma_f32 v26, v7, s45, -v20
	v_rndne_f32_e32 v27, v20
	v_fma_f32 v28, v6, s45, -v21
	v_rndne_f32_e32 v29, v21
	v_fmac_f32_e32 v22, 0xb2a5705f, v15
	v_sub_f32_e32 v18, v18, v23
	v_fmac_f32_e32 v24, 0xb2a5705f, v14
	v_sub_f32_e32 v19, v19, v25
	v_fmac_f32_e32 v26, 0xb2a5705f, v7
	v_sub_f32_e32 v20, v20, v27
	v_fmac_f32_e32 v28, 0xb2a5705f, v6
	v_sub_f32_e32 v21, v21, v29
	v_add_f32_e32 v18, v18, v22
	v_add_f32_e32 v19, v19, v24
	v_cvt_i32_f32_e32 v23, v23
	v_cvt_i32_f32_e32 v25, v25
	v_add_f32_e32 v20, v20, v26
	v_add_f32_e32 v21, v21, v28
	v_exp_f32_e32 v18, v18
	v_exp_f32_e32 v19, v19
	v_cvt_i32_f32_e32 v27, v27
	v_cvt_i32_f32_e32 v29, v29
	v_exp_f32_e32 v20, v20
	v_exp_f32_e32 v21, v21
	v_ldexp_f32 v18, v18, v23
	v_ldexp_f32 v19, v19, v25
	v_cmp_nlt_f32_e32 vcc, s51, v14
	v_cmp_nlt_f32_e64 s[16:17], s51, v15
	v_ldexp_f32 v20, v20, v27
	v_cmp_nlt_f32_e64 s[0:1], s51, v7
	v_ldexp_f32 v21, v21, v29
	v_cmp_nlt_f32_e64 s[14:15], s51, v6
	v_cndmask_b32_e64 v18, 0, v18, s[16:17]
	v_cndmask_b32_e32 v19, 0, v19, vcc
	v_cmp_ngt_f32_e32 vcc, s53, v14
	v_cmp_ngt_f32_e64 s[16:17], s53, v15
	v_cndmask_b32_e64 v14, 0, v20, s[0:1]
	v_cmp_ngt_f32_e64 s[0:1], s53, v7
	v_cndmask_b32_e64 v20, 0, v21, s[14:15]
	v_cmp_ngt_f32_e64 s[14:15], s53, v6
	v_cndmask_b32_e64 v7, v209, v18, s[16:17]
	v_cndmask_b32_e32 v6, v209, v19, vcc
	v_cndmask_b32_e64 v15, v209, v14, s[0:1]
	v_cndmask_b32_e64 v14, v209, v20, s[14:15]
	v_pk_add_f32 v[6:7], v[6:7], 1.0 op_sel_hi:[1,0] neg_lo:[1,0] neg_hi:[1,0]
	v_cmp_lt_f32_e64 vcc, |v13|, 1.0
	v_cmp_lt_f32_e64 s[16:17], |v12|, 1.0
	v_pk_add_f32 v[14:15], v[14:15], 1.0 op_sel_hi:[1,0] neg_lo:[1,0] neg_hi:[1,0]
	v_cmp_lt_f32_e64 s[0:1], |v5|, 1.0
	v_cmp_lt_f32_e64 s[14:15], |v4|, 1.0
	v_cndmask_b32_e64 v6, v6, v16, s[16:17]
	v_cndmask_b32_e32 v7, v7, v17, vcc
	v_cndmask_b32_e64 v8, v14, v8, s[14:15]
	v_cndmask_b32_e64 v9, v15, v9, s[0:1]
	v_bfi_b32 v7, s43, v7, v13
	v_bfi_b32 v6, s43, v6, v12
	v_bfi_b32 v5, s43, v9, v5
	v_bfi_b32 v4, s43, v8, v4
	v_pk_add_f32 v[6:7], v[6:7], 1.0 op_sel_hi:[1,0]
	v_pk_add_f32 v[4:5], v[4:5], 1.0 op_sel_hi:[1,0]
	v_pk_mul_f32 v[6:7], v[10:11], v[6:7]
	v_pk_mul_f32 v[2:3], v[2:3], v[4:5]
	ds_write_b32 v32, v6
	ds_write_b32 v33, v7
	ds_write_b32 v32, v2 offset:4
	ds_write_b32 v33, v3 offset:4
	s_cbranch_scc1 .LBB0_931
	ds_read_b128 v[6:9], v189
	ds_read_b128 v[22:25], v189 offset:16
	ds_read_b128 v[38:41], v189 offset:32
	ds_read_b128 v[54:57], v189 offset:48
	v_lshlrev_b64 v[64:65], 12, v[176:177]
	s_waitcnt lgkmcnt(3)
	s_waitcnt lgkmcnt(2)
	s_waitcnt lgkmcnt(1)
	s_waitcnt lgkmcnt(0)
	v_lshl_or_b32 v4, v7, 7, v137
	v_lshl_or_b32 v0, v6, 7, v174
	v_lshl_or_b32 v12, v9, 7, v137
	v_lshl_or_b32 v8, v8, 7, v174
	v_lshl_or_b32 v20, v23, 7, v137
	v_lshl_or_b32 v16, v22, 7, v174
	v_lshl_or_b32 v28, v25, 7, v137
	v_lshl_or_b32 v24, v24, 7, v174
	v_lshl_or_b32 v36, v39, 7, v137
	v_lshl_or_b32 v32, v38, 7, v174
	v_lshl_or_b32 v44, v41, 7, v137
	v_lshl_or_b32 v40, v40, 7, v174
	v_lshl_or_b32 v52, v55, 7, v137
	v_lshl_or_b32 v48, v54, 7, v174
	v_lshl_or_b32 v60, v57, 7, v137
	v_lshl_or_b32 v56, v56, 7, v174
	v_lshl_add_u64 v[66:67], v[148:149], 0, v[64:65]
	global_load_dwordx4 v[0:3], v0, s[38:39]
	s_nop 0
	global_load_dwordx4 v[4:7], v4, s[38:39]
	s_nop 0
	global_load_dwordx4 v[8:11], v8, s[38:39]
	s_nop 0
	global_load_dwordx4 v[12:15], v12, s[38:39]
	s_nop 0
	global_load_dwordx4 v[16:19], v16, s[38:39]
	s_nop 0
	global_load_dwordx4 v[20:23], v20, s[38:39]
	s_nop 0
	global_load_dwordx4 v[24:27], v24, s[38:39]
	s_nop 0
	global_load_dwordx4 v[28:31], v28, s[38:39]
	s_nop 0
	global_load_dwordx4 v[32:35], v32, s[38:39]
	s_nop 0
	global_load_dwordx4 v[36:39], v36, s[38:39]
	s_nop 0
	global_load_dwordx4 v[40:43], v40, s[38:39]
	s_nop 0
	global_load_dwordx4 v[44:47], v44, s[38:39]
	s_nop 0
	global_load_dwordx4 v[48:51], v48, s[38:39]
	s_nop 0
	global_load_dwordx4 v[52:55], v52, s[38:39]
	s_nop 0
	global_load_dwordx4 v[56:59], v56, s[38:39]
	s_nop 0
	global_load_dwordx4 v[60:63], v60, s[38:39]
	v_lshlrev_b32_e32 v252, 7, v175
	v_add_u32_e32 v252, 0x20010, v252
	s_nop 0
	v_readfirstlane_b32 s100, v252
	v_add_u32_e32 v252, v136, v252
	v_lshrrev_b32_e32 v253, 2, v136
	v_lshrrev_b32_e32 v254, 4, v253
	v_add_u32_e32 v254, v176, v254
	v_lshlrev_b32_e32 v254, 12, v254
	v_and_b32_e32 v253, 15, v253
	v_lshl_or_b32 v254, v253, 4, v254
	s_mov_b32 m0, s100
	s_nop 0
	global_load_lds_dwordx4 v254, s[80:81]
	s_add_i32 m0, s100, 0x400
	s_nop 0
	global_load_lds_dwordx4 v254, s[28:29]
	v_mbcnt_lo_u32_b32 v68, -1, 0
	v_mbcnt_hi_u32_b32 v68, -1, v68
	v_and_b32_e32 v68, 15, v68
	v_add_u32_e32 v68, v68, v176
	v_mov_b32_e32 v69, v139
	v_lshl_add_u64 v[68:69], v[68:69], 3, s[26:27]
	global_load_dwordx2 v[248:249], v[68:69], off
	s_waitcnt vmcnt(0)
	v_mov_b32_e32 v138, v139
	s_mov_b32 s0, 0
	s_mov_b32 s16, 16
	s_movk_i32 s17, 0x100
	s_mov_b32 s34, 0x40000
	v_mov_b64_e32 v[178:179], v[138:139]
	v_mov_b64_e32 v[180:181], v[138:139]
	s_branch .LBB0_934
.LBB0_933:
	s_and_b32 s101, s59, 3
	v_lshl_add_u32 v253, s101, 8, v252
	ds_read_b32 v212, v253
	ds_read_b32 v213, v253 offset:1024
	v_cvt_pk_f32_fp8_e32 v[222:223], v124
	v_cvt_pk_f32_fp8_sdwa v[224:225], v124 src0_sel:WORD_1
	v_cvt_pk_f32_fp8_e32 v[226:227], v125
	v_cvt_pk_f32_fp8_sdwa v[124:125], v125 src0_sel:WORD_1
	v_lshl_add_u32 v128, s59, 9, v193
	v_cvt_pk_f32_fp8_e32 v[234:235], v120
	v_cvt_pk_f32_fp8_sdwa v[236:237], v120 src0_sel:WORD_1
	v_cvt_pk_f32_fp8_e32 v[238:239], v121
	v_cvt_pk_f32_fp8_sdwa v[120:121], v121 src0_sel:WORD_1
	ds_read_b128 v[132:135], v128
	ds_read_b128 v[214:217], v128 offset:16
	ds_read_b128 v[218:221], v128 offset:32
	ds_read_b128 v[128:131], v128 offset:48
	v_cvt_pk_f32_fp8_e32 v[228:229], v126
	s_waitcnt lgkmcnt(3)
	v_pk_fma_f32 v[222:223], v[132:133], v[222:223], 0 op_sel_hi:[0,1,0]
	v_pk_fma_f32 v[224:225], v[132:133], v[224:225], 0 op_sel_hi:[0,1,0]
	v_pk_fma_f32 v[124:125], v[132:133], v[124:125], 0 op_sel_hi:[0,1,0]
	v_cvt_pk_f32_fp8_sdwa v[230:231], v126 src0_sel:WORD_1
	v_cvt_pk_f32_fp8_e32 v[232:233], v127
	v_cvt_pk_f32_fp8_sdwa v[126:127], v127 src0_sel:WORD_1
	v_pk_fma_f32 v[222:223], v[132:133], v[234:235], v[222:223] op_sel:[1,0,0]
	v_pk_fma_f32 v[224:225], v[132:133], v[236:237], v[224:225] op_sel:[1,0,0]
	v_pk_fma_f32 v[120:121], v[132:133], v[120:121], v[124:125] op_sel:[1,0,0]
	v_cvt_pk_f32_fp8_e32 v[124:125], v122
	v_cvt_pk_f32_fp8_sdwa v[234:235], v122 src0_sel:WORD_1
	v_cvt_pk_f32_fp8_e32 v[236:237], v123
	v_cvt_pk_f32_fp8_sdwa v[122:123], v123 src0_sel:WORD_1
	v_pk_fma_f32 v[226:227], v[132:133], v[226:227], 0 op_sel_hi:[0,1,0]
	v_pk_fma_f32 v[228:229], v[132:133], v[228:229], 0 op_sel_hi:[0,1,0]
	v_pk_fma_f32 v[230:231], v[132:133], v[230:231], 0 op_sel_hi:[0,1,0]
	v_pk_fma_f32 v[232:233], v[132:133], v[232:233], 0 op_sel_hi:[0,1,0]
	v_pk_fma_f32 v[126:127], v[132:133], v[126:127], 0 op_sel_hi:[0,1,0]
	v_pk_fma_f32 v[226:227], v[132:133], v[238:239], v[226:227] op_sel:[1,0,0]
	v_pk_fma_f32 v[124:125], v[132:133], v[124:125], v[228:229] op_sel:[1,0,0]
	v_pk_fma_f32 v[228:229], v[132:133], v[234:235], v[230:231] op_sel:[1,0,0]
	v_pk_fma_f32 v[230:231], v[132:133], v[236:237], v[232:233] op_sel:[1,0,0]
	v_pk_fma_f32 v[122:123], v[132:133], v[122:123], v[126:127] op_sel:[1,0,0]
	v_cvt_pk_f32_fp8_e32 v[126:127], v116
	v_cvt_pk_f32_fp8_sdwa v[132:133], v116 src0_sel:WORD_1
	v_cvt_pk_f32_fp8_e32 v[232:233], v117
	v_cvt_pk_f32_fp8_sdwa v[116:117], v117 src0_sel:WORD_1
	v_pk_fma_f32 v[126:127], v[134:135], v[126:127], v[222:223] op_sel_hi:[0,1,1]
	v_pk_fma_f32 v[132:133], v[134:135], v[132:133], v[224:225] op_sel_hi:[0,1,1]
	v_pk_fma_f32 v[222:223], v[134:135], v[232:233], v[226:227] op_sel_hi:[0,1,1]
	v_pk_fma_f32 v[116:117], v[134:135], v[116:117], v[120:121] op_sel_hi:[0,1,1]
	v_cvt_pk_f32_fp8_e32 v[120:121], v118
	v_cvt_pk_f32_fp8_sdwa v[224:225], v118 src0_sel:WORD_1
	v_cvt_pk_f32_fp8_e32 v[226:227], v119
	v_cvt_pk_f32_fp8_sdwa v[118:119], v119 src0_sel:WORD_1
	v_pk_fma_f32 v[120:121], v[134:135], v[120:121], v[124:125] op_sel_hi:[0,1,1]
	v_pk_fma_f32 v[124:125], v[134:135], v[224:225], v[228:229] op_sel_hi:[0,1,1]
	v_pk_fma_f32 v[224:225], v[134:135], v[226:227], v[230:231] op_sel_hi:[0,1,1]
	v_pk_fma_f32 v[118:119], v[134:135], v[118:119], v[122:123] op_sel_hi:[0,1,1]
	v_mov_b32_e32 v122, v135
	v_cvt_pk_f32_fp8_e32 v[134:135], v112
	v_cvt_pk_f32_fp8_sdwa v[226:227], v112 src0_sel:WORD_1
	v_cvt_pk_f32_fp8_e32 v[228:229], v113
	v_cvt_pk_f32_fp8_sdwa v[112:113], v113 src0_sel:WORD_1
	v_pk_fma_f32 v[126:127], v[122:123], v[134:135], v[126:127] op_sel_hi:[0,1,1]
	v_pk_fma_f32 v[132:133], v[122:123], v[226:227], v[132:133] op_sel_hi:[0,1,1]
	v_pk_fma_f32 v[134:135], v[122:123], v[228:229], v[222:223] op_sel_hi:[0,1,1]
	v_pk_fma_f32 v[112:113], v[122:123], v[112:113], v[116:117] op_sel_hi:[0,1,1]
	v_cvt_pk_f32_fp8_e32 v[116:117], v114
	v_cvt_pk_f32_fp8_sdwa v[222:223], v114 src0_sel:WORD_1
	v_cvt_pk_f32_fp8_e32 v[226:227], v115
	v_cvt_pk_f32_fp8_sdwa v[114:115], v115 src0_sel:WORD_1
	v_pk_fma_f32 v[116:117], v[122:123], v[116:117], v[120:121] op_sel_hi:[0,1,1]
	v_pk_fma_f32 v[120:121], v[122:123], v[222:223], v[124:125] op_sel_hi:[0,1,1]
	v_pk_fma_f32 v[124:125], v[122:123], v[226:227], v[224:225] op_sel_hi:[0,1,1]
	v_pk_fma_f32 v[114:115], v[122:123], v[114:115], v[118:119] op_sel_hi:[0,1,1]
	v_cvt_pk_f32_fp8_e32 v[118:119], v108
	v_cvt_pk_f32_fp8_sdwa v[122:123], v108 src0_sel:WORD_1
	v_cvt_pk_f32_fp8_e32 v[222:223], v109
	v_cvt_pk_f32_fp8_sdwa v[108:109], v109 src0_sel:WORD_1
	s_waitcnt lgkmcnt(2)
	v_pk_fma_f32 v[118:119], v[214:215], v[118:119], v[126:127] op_sel_hi:[0,1,1]
	v_pk_fma_f32 v[122:123], v[214:215], v[122:123], v[132:133] op_sel_hi:[0,1,1]
	v_pk_fma_f32 v[126:127], v[214:215], v[222:223], v[134:135] op_sel_hi:[0,1,1]
	v_pk_fma_f32 v[108:109], v[214:215], v[108:109], v[112:113] op_sel_hi:[0,1,1]
	v_cvt_pk_f32_fp8_e32 v[112:113], v110
	v_cvt_pk_f32_fp8_sdwa v[132:133], v110 src0_sel:WORD_1
	v_cvt_pk_f32_fp8_e32 v[134:135], v111
	v_cvt_pk_f32_fp8_sdwa v[110:111], v111 src0_sel:WORD_1
	v_pk_fma_f32 v[112:113], v[214:215], v[112:113], v[116:117] op_sel_hi:[0,1,1]
	v_pk_fma_f32 v[116:117], v[214:215], v[132:133], v[120:121] op_sel_hi:[0,1,1]
	v_pk_fma_f32 v[120:121], v[214:215], v[134:135], v[124:125] op_sel_hi:[0,1,1]
	v_pk_fma_f32 v[110:111], v[214:215], v[110:111], v[114:115] op_sel_hi:[0,1,1]
	v_cvt_pk_f32_fp8_e32 v[114:115], v104
	v_cvt_pk_f32_fp8_sdwa v[124:125], v104 src0_sel:WORD_1
	v_cvt_pk_f32_fp8_e32 v[132:133], v105
	v_cvt_pk_f32_fp8_sdwa v[104:105], v105 src0_sel:WORD_1
	v_pk_fma_f32 v[114:115], v[214:215], v[114:115], v[118:119] op_sel:[1,0,0]
	v_pk_fma_f32 v[118:119], v[214:215], v[124:125], v[122:123] op_sel:[1,0,0]
	v_pk_fma_f32 v[122:123], v[214:215], v[132:133], v[126:127] op_sel:[1,0,0]
	v_pk_fma_f32 v[104:105], v[214:215], v[104:105], v[108:109] op_sel:[1,0,0]
	v_cvt_pk_f32_fp8_e32 v[108:109], v106
	v_cvt_pk_f32_fp8_sdwa v[124:125], v106 src0_sel:WORD_1
	v_cvt_pk_f32_fp8_e32 v[126:127], v107
	v_cvt_pk_f32_fp8_sdwa v[106:107], v107 src0_sel:WORD_1
	v_pk_fma_f32 v[108:109], v[214:215], v[108:109], v[112:113] op_sel:[1,0,0]
	v_pk_fma_f32 v[112:113], v[214:215], v[124:125], v[116:117] op_sel:[1,0,0]
	v_pk_fma_f32 v[116:117], v[214:215], v[126:127], v[120:121] op_sel:[1,0,0]
	v_pk_fma_f32 v[106:107], v[214:215], v[106:107], v[110:111] op_sel:[1,0,0]
	v_cvt_pk_f32_fp8_e32 v[110:111], v100
	v_cvt_pk_f32_fp8_sdwa v[120:121], v100 src0_sel:WORD_1
	v_cvt_pk_f32_fp8_e32 v[124:125], v101
	v_cvt_pk_f32_fp8_sdwa v[100:101], v101 src0_sel:WORD_1
	v_pk_fma_f32 v[110:111], v[216:217], v[110:111], v[114:115] op_sel_hi:[0,1,1]
	v_pk_fma_f32 v[114:115], v[216:217], v[120:121], v[118:119] op_sel_hi:[0,1,1]
	v_pk_fma_f32 v[118:119], v[216:217], v[124:125], v[122:123] op_sel_hi:[0,1,1]
	v_pk_fma_f32 v[100:101], v[216:217], v[100:101], v[104:105] op_sel_hi:[0,1,1]
	v_cvt_pk_f32_fp8_e32 v[104:105], v102
	v_cvt_pk_f32_fp8_sdwa v[120:121], v102 src0_sel:WORD_1
	v_cvt_pk_f32_fp8_e32 v[122:123], v103
	v_cvt_pk_f32_fp8_sdwa v[102:103], v103 src0_sel:WORD_1
	v_pk_fma_f32 v[104:105], v[216:217], v[104:105], v[108:109] op_sel_hi:[0,1,1]
	v_pk_fma_f32 v[108:109], v[216:217], v[120:121], v[112:113] op_sel_hi:[0,1,1]
	v_pk_fma_f32 v[112:113], v[216:217], v[122:123], v[116:117] op_sel_hi:[0,1,1]
	v_cvt_pk_f32_fp8_e32 v[116:117], v96
	v_cvt_pk_f32_fp8_sdwa v[120:121], v96 src0_sel:WORD_1
	v_cvt_pk_f32_fp8_e32 v[122:123], v97
	v_cvt_pk_f32_fp8_sdwa v[96:97], v97 src0_sel:WORD_1
	v_pk_fma_f32 v[102:103], v[216:217], v[102:103], v[106:107] op_sel_hi:[0,1,1]
	v_mov_b32_e32 v106, v217
	v_pk_fma_f32 v[110:111], v[106:107], v[116:117], v[110:111] op_sel_hi:[0,1,1]
	v_pk_fma_f32 v[114:115], v[106:107], v[120:121], v[114:115] op_sel_hi:[0,1,1]
	v_pk_fma_f32 v[116:117], v[106:107], v[122:123], v[118:119] op_sel_hi:[0,1,1]
	v_pk_fma_f32 v[96:97], v[106:107], v[96:97], v[100:101] op_sel_hi:[0,1,1]
	v_cvt_pk_f32_fp8_e32 v[100:101], v98
	v_cvt_pk_f32_fp8_sdwa v[118:119], v98 src0_sel:WORD_1
	v_cvt_pk_f32_fp8_e32 v[120:121], v99
	v_cvt_pk_f32_fp8_sdwa v[98:99], v99 src0_sel:WORD_1
	v_pk_fma_f32 v[100:101], v[106:107], v[100:101], v[104:105] op_sel_hi:[0,1,1]
	v_pk_fma_f32 v[104:105], v[106:107], v[118:119], v[108:109] op_sel_hi:[0,1,1]
	v_pk_fma_f32 v[108:109], v[106:107], v[120:121], v[112:113] op_sel_hi:[0,1,1]
	v_pk_fma_f32 v[98:99], v[106:107], v[98:99], v[102:103] op_sel_hi:[0,1,1]
	v_cvt_pk_f32_fp8_e32 v[102:103], v92
	v_cvt_pk_f32_fp8_sdwa v[106:107], v92 src0_sel:WORD_1
	v_cvt_pk_f32_fp8_e32 v[112:113], v93
	v_cvt_pk_f32_fp8_sdwa v[92:93], v93 src0_sel:WORD_1
	s_waitcnt lgkmcnt(1)
	v_pk_fma_f32 v[102:103], v[218:219], v[102:103], v[110:111] op_sel_hi:[0,1,1]
	v_pk_fma_f32 v[106:107], v[218:219], v[106:107], v[114:115] op_sel_hi:[0,1,1]
	v_pk_fma_f32 v[110:111], v[218:219], v[112:113], v[116:117] op_sel_hi:[0,1,1]
	v_pk_fma_f32 v[92:93], v[218:219], v[92:93], v[96:97] op_sel_hi:[0,1,1]
	v_cvt_pk_f32_fp8_e32 v[96:97], v94
	v_cvt_pk_f32_fp8_sdwa v[112:113], v94 src0_sel:WORD_1
	v_cvt_pk_f32_fp8_e32 v[114:115], v95
	v_cvt_pk_f32_fp8_sdwa v[94:95], v95 src0_sel:WORD_1
	v_pk_fma_f32 v[96:97], v[218:219], v[96:97], v[100:101] op_sel_hi:[0,1,1]
	v_pk_fma_f32 v[100:101], v[218:219], v[112:113], v[104:105] op_sel_hi:[0,1,1]
	v_pk_fma_f32 v[104:105], v[218:219], v[114:115], v[108:109] op_sel_hi:[0,1,1]
	v_pk_fma_f32 v[94:95], v[218:219], v[94:95], v[98:99] op_sel_hi:[0,1,1]
	v_cvt_pk_f32_fp8_e32 v[98:99], v88
	v_cvt_pk_f32_fp8_sdwa v[108:109], v88 src0_sel:WORD_1
	v_cvt_pk_f32_fp8_e32 v[112:113], v89
	v_cvt_pk_f32_fp8_sdwa v[88:89], v89 src0_sel:WORD_1
	v_pk_fma_f32 v[98:99], v[218:219], v[98:99], v[102:103] op_sel:[1,0,0]
	v_pk_fma_f32 v[102:103], v[218:219], v[108:109], v[106:107] op_sel:[1,0,0]
	v_pk_fma_f32 v[106:107], v[218:219], v[112:113], v[110:111] op_sel:[1,0,0]
	v_pk_fma_f32 v[88:89], v[218:219], v[88:89], v[92:93] op_sel:[1,0,0]
	v_cvt_pk_f32_fp8_e32 v[92:93], v90
	v_cvt_pk_f32_fp8_sdwa v[108:109], v90 src0_sel:WORD_1
	v_cvt_pk_f32_fp8_e32 v[110:111], v91
	v_cvt_pk_f32_fp8_sdwa v[90:91], v91 src0_sel:WORD_1
	v_pk_fma_f32 v[92:93], v[218:219], v[92:93], v[96:97] op_sel:[1,0,0]
	v_pk_fma_f32 v[96:97], v[218:219], v[108:109], v[100:101] op_sel:[1,0,0]
	v_pk_fma_f32 v[100:101], v[218:219], v[110:111], v[104:105] op_sel:[1,0,0]
	v_pk_fma_f32 v[90:91], v[218:219], v[90:91], v[94:95] op_sel:[1,0,0]
	v_cvt_pk_f32_fp8_e32 v[94:95], v84
	v_cvt_pk_f32_fp8_sdwa v[104:105], v84 src0_sel:WORD_1
	v_cvt_pk_f32_fp8_e32 v[108:109], v85
	v_cvt_pk_f32_fp8_sdwa v[84:85], v85 src0_sel:WORD_1
	v_pk_fma_f32 v[94:95], v[220:221], v[94:95], v[98:99] op_sel_hi:[0,1,1]
	v_pk_fma_f32 v[98:99], v[220:221], v[104:105], v[102:103] op_sel_hi:[0,1,1]
	v_pk_fma_f32 v[102:103], v[220:221], v[108:109], v[106:107] op_sel_hi:[0,1,1]
	v_pk_fma_f32 v[84:85], v[220:221], v[84:85], v[88:89] op_sel_hi:[0,1,1]
	v_cvt_pk_f32_fp8_e32 v[88:89], v86
	v_cvt_pk_f32_fp8_sdwa v[104:105], v86 src0_sel:WORD_1
	v_cvt_pk_f32_fp8_e32 v[106:107], v87
	v_cvt_pk_f32_fp8_sdwa v[86:87], v87 src0_sel:WORD_1
	v_pk_fma_f32 v[88:89], v[220:221], v[88:89], v[92:93] op_sel_hi:[0,1,1]
	v_pk_fma_f32 v[92:93], v[220:221], v[104:105], v[96:97] op_sel_hi:[0,1,1]
	v_pk_fma_f32 v[96:97], v[220:221], v[106:107], v[100:101] op_sel_hi:[0,1,1]
	v_cvt_pk_f32_fp8_e32 v[100:101], v80
	v_cvt_pk_f32_fp8_sdwa v[104:105], v80 src0_sel:WORD_1
	v_cvt_pk_f32_fp8_e32 v[106:107], v81
	v_cvt_pk_f32_fp8_sdwa v[80:81], v81 src0_sel:WORD_1
	v_pk_fma_f32 v[86:87], v[220:221], v[86:87], v[90:91] op_sel_hi:[0,1,1]
	v_mov_b32_e32 v90, v221
	v_pk_fma_f32 v[94:95], v[90:91], v[100:101], v[94:95] op_sel_hi:[0,1,1]
	v_pk_fma_f32 v[98:99], v[90:91], v[104:105], v[98:99] op_sel_hi:[0,1,1]
	v_pk_fma_f32 v[100:101], v[90:91], v[106:107], v[102:103] op_sel_hi:[0,1,1]
	v_pk_fma_f32 v[80:81], v[90:91], v[80:81], v[84:85] op_sel_hi:[0,1,1]
	v_cvt_pk_f32_fp8_e32 v[84:85], v82
	v_cvt_pk_f32_fp8_sdwa v[102:103], v82 src0_sel:WORD_1
	v_cvt_pk_f32_fp8_e32 v[104:105], v83
	v_cvt_pk_f32_fp8_sdwa v[82:83], v83 src0_sel:WORD_1
	v_pk_fma_f32 v[84:85], v[90:91], v[84:85], v[88:89] op_sel_hi:[0,1,1]
	v_pk_fma_f32 v[88:89], v[90:91], v[102:103], v[92:93] op_sel_hi:[0,1,1]
	v_pk_fma_f32 v[92:93], v[90:91], v[104:105], v[96:97] op_sel_hi:[0,1,1]
	v_pk_fma_f32 v[82:83], v[90:91], v[82:83], v[86:87] op_sel_hi:[0,1,1]
	v_cvt_pk_f32_fp8_e32 v[86:87], v76
	v_cvt_pk_f32_fp8_sdwa v[90:91], v76 src0_sel:WORD_1
	v_cvt_pk_f32_fp8_e32 v[96:97], v77
	v_cvt_pk_f32_fp8_sdwa v[76:77], v77 src0_sel:WORD_1
	s_waitcnt lgkmcnt(0)
	s_and_b32 s101, s61, 2
	s_cmp_lg_u32 s101, 0
	s_cbranch_scc1 .Lvx_skip
	s_and_b32 s98, s61, 12
	s_lshl_b32 s98, s98, 12
	s_lshr_b32 s101, s61, 4
	s_lshl_b32 s101, s101, 8
	s_add_i32 s98, s98, s101
	v_add_u32_e32 v253, s98, v254
	s_mov_b32 m0, s100
	s_nop 0
	global_load_lds_dwordx4 v253, s[80:81]
	s_add_i32 m0, s100, 0x400
	s_nop 0
	global_load_lds_dwordx4 v253, s[28:29]
.Lvx_skip:
	v_pk_fma_f32 v[86:87], v[128:129], v[86:87], v[94:95] op_sel_hi:[0,1,1]
	v_pk_fma_f32 v[90:91], v[128:129], v[90:91], v[98:99] op_sel_hi:[0,1,1]
	v_pk_fma_f32 v[94:95], v[128:129], v[96:97], v[100:101] op_sel_hi:[0,1,1]
	v_pk_fma_f32 v[76:77], v[128:129], v[76:77], v[80:81] op_sel_hi:[0,1,1]
	v_cvt_pk_f32_fp8_e32 v[80:81], v78
	v_cvt_pk_f32_fp8_sdwa v[96:97], v78 src0_sel:WORD_1
	v_cvt_pk_f32_fp8_e32 v[98:99], v79
	v_cvt_pk_f32_fp8_sdwa v[78:79], v79 src0_sel:WORD_1
	v_pk_fma_f32 v[80:81], v[128:129], v[80:81], v[84:85] op_sel_hi:[0,1,1]
	v_pk_fma_f32 v[84:85], v[128:129], v[96:97], v[88:89] op_sel_hi:[0,1,1]
	v_pk_fma_f32 v[88:89], v[128:129], v[98:99], v[92:93] op_sel_hi:[0,1,1]
	v_pk_fma_f32 v[78:79], v[128:129], v[78:79], v[82:83] op_sel_hi:[0,1,1]
	v_cvt_pk_f32_fp8_e32 v[82:83], v72
	v_cvt_pk_f32_fp8_sdwa v[92:93], v72 src0_sel:WORD_1
	v_cvt_pk_f32_fp8_e32 v[96:97], v73
	v_cvt_pk_f32_fp8_sdwa v[72:73], v73 src0_sel:WORD_1
	v_pk_fma_f32 v[82:83], v[128:129], v[82:83], v[86:87] op_sel:[1,0,0]
	v_pk_fma_f32 v[86:87], v[128:129], v[92:93], v[90:91] op_sel:[1,0,0]
	v_pk_fma_f32 v[90:91], v[128:129], v[96:97], v[94:95] op_sel:[1,0,0]
	v_pk_fma_f32 v[72:73], v[128:129], v[72:73], v[76:77] op_sel:[1,0,0]
	v_cvt_pk_f32_fp8_e32 v[76:77], v74
	v_cvt_pk_f32_fp8_sdwa v[92:93], v74 src0_sel:WORD_1
	v_cvt_pk_f32_fp8_e32 v[94:95], v75
	v_cvt_pk_f32_fp8_sdwa v[74:75], v75 src0_sel:WORD_1
	v_pk_fma_f32 v[76:77], v[128:129], v[76:77], v[80:81] op_sel:[1,0,0]
	v_pk_fma_f32 v[80:81], v[128:129], v[92:93], v[84:85] op_sel:[1,0,0]
	v_pk_fma_f32 v[84:85], v[128:129], v[94:95], v[88:89] op_sel:[1,0,0]
	v_pk_fma_f32 v[74:75], v[128:129], v[74:75], v[78:79] op_sel:[1,0,0]
	v_cvt_pk_f32_fp8_e32 v[78:79], v68
	v_cvt_pk_f32_fp8_sdwa v[88:89], v68 src0_sel:WORD_1
	v_cvt_pk_f32_fp8_e32 v[92:93], v69
	v_cvt_pk_f32_fp8_sdwa v[68:69], v69 src0_sel:WORD_1
	v_pk_fma_f32 v[78:79], v[130:131], v[78:79], v[82:83] op_sel_hi:[0,1,1]
	v_pk_fma_f32 v[82:83], v[130:131], v[88:89], v[86:87] op_sel_hi:[0,1,1]
	v_pk_fma_f32 v[86:87], v[130:131], v[92:93], v[90:91] op_sel_hi:[0,1,1]
	v_pk_fma_f32 v[68:69], v[130:131], v[68:69], v[72:73] op_sel_hi:[0,1,1]
	v_cvt_pk_f32_fp8_e32 v[72:73], v70
	v_cvt_pk_f32_fp8_sdwa v[88:89], v70 src0_sel:WORD_1
	v_cvt_pk_f32_fp8_e32 v[90:91], v71
	v_cvt_pk_f32_fp8_sdwa v[70:71], v71 src0_sel:WORD_1
	v_pk_fma_f32 v[72:73], v[130:131], v[72:73], v[76:77] op_sel_hi:[0,1,1]
	v_pk_fma_f32 v[76:77], v[130:131], v[88:89], v[80:81] op_sel_hi:[0,1,1]
	v_pk_fma_f32 v[80:81], v[130:131], v[90:91], v[84:85] op_sel_hi:[0,1,1]
	v_cvt_pk_f32_fp8_e32 v[84:85], v64
	v_cvt_pk_f32_fp8_sdwa v[88:89], v64 src0_sel:WORD_1
	v_cvt_pk_f32_fp8_e32 v[90:91], v65
	v_cvt_pk_f32_fp8_sdwa v[64:65], v65 src0_sel:WORD_1
	v_pk_fma_f32 v[70:71], v[130:131], v[70:71], v[74:75] op_sel_hi:[0,1,1]
	v_mov_b32_e32 v74, v131
	v_pk_fma_f32 v[78:79], v[74:75], v[84:85], v[78:79] op_sel_hi:[0,1,1]
	v_pk_fma_f32 v[64:65], v[74:75], v[64:65], v[68:69] op_sel_hi:[0,1,1]
	v_cvt_pk_f32_fp8_e32 v[68:69], v66
	v_pk_fma_f32 v[82:83], v[74:75], v[88:89], v[82:83] op_sel_hi:[0,1,1]
	v_pk_fma_f32 v[84:85], v[74:75], v[90:91], v[86:87] op_sel_hi:[0,1,1]
	v_cvt_pk_f32_fp8_sdwa v[86:87], v66 src0_sel:WORD_1
	v_cvt_pk_f32_fp8_e32 v[88:89], v67
	v_cvt_pk_f32_fp8_sdwa v[66:67], v67 src0_sel:WORD_1
	v_pk_fma_f32 v[68:69], v[74:75], v[68:69], v[72:73] op_sel_hi:[0,1,1]
	v_pk_fma_f32 v[72:73], v[74:75], v[86:87], v[76:77] op_sel_hi:[0,1,1]
	v_pk_fma_f32 v[76:77], v[74:75], v[88:89], v[80:81] op_sel_hi:[0,1,1]
	v_pk_fma_f32 v[66:67], v[74:75], v[66:67], v[70:71] op_sel_hi:[0,1,1]
	v_cndmask_b32_e64 v70, v78, v68, s[8:9]
	v_cndmask_b32_e64 v71, v79, v69, s[8:9]
	ds_bpermute_b32 v70, v204, v70
	ds_bpermute_b32 v71, v204, v71
	v_cndmask_b32_e64 v74, v82, v72, s[8:9]
	v_cndmask_b32_e64 v75, v83, v73, s[8:9]
	v_cndmask_b32_e64 v80, v84, v76, s[8:9]
	v_cndmask_b32_e64 v81, v85, v77, s[8:9]
	v_cndmask_b32_e64 v86, v64, v66, s[8:9]
	v_cndmask_b32_e64 v87, v65, v67, s[8:9]
	ds_bpermute_b32 v74, v204, v74
	ds_bpermute_b32 v75, v204, v75
	ds_bpermute_b32 v80, v204, v80
	ds_bpermute_b32 v81, v204, v81
	ds_bpermute_b32 v86, v204, v86
	ds_bpermute_b32 v87, v204, v87
	v_cndmask_b32_e64 v69, v69, v79, s[8:9]
	v_cndmask_b32_e64 v68, v68, v78, s[8:9]
	s_waitcnt lgkmcnt(6)
	v_pk_add_f32 v[68:69], v[68:69], v[70:71]
	v_cndmask_b32_e64 v71, v73, v83, s[8:9]
	v_cndmask_b32_e64 v70, v72, v82, s[8:9]
	v_cndmask_b32_e64 v73, v77, v85, s[8:9]
	v_cndmask_b32_e64 v72, v76, v84, s[8:9]
	v_cndmask_b32_e64 v65, v67, v65, s[8:9]
	v_cndmask_b32_e64 v64, v66, v64, s[8:9]
	s_waitcnt lgkmcnt(4)
	v_pk_add_f32 v[70:71], v[70:71], v[74:75]
	s_waitcnt lgkmcnt(2)
	v_pk_add_f32 v[72:73], v[72:73], v[80:81]
	s_waitcnt lgkmcnt(0)
	v_pk_add_f32 v[64:65], v[64:65], v[86:87]
	v_cndmask_b32_e64 v75, v73, v69, s[10:11]
	v_cndmask_b32_e64 v67, v69, v73, s[10:11]
	v_cndmask_b32_e64 v69, v70, v64, s[10:11]
	v_cndmask_b32_e64 v66, v68, v72, s[10:11]
	ds_bpermute_b32 v76, v205, v69
	v_cndmask_b32_e64 v69, v71, v65, s[10:11]
	ds_bpermute_b32 v66, v205, v66
	ds_bpermute_b32 v67, v205, v67
	ds_bpermute_b32 v77, v205, v69
	v_cndmask_b32_e64 v74, v72, v68, s[10:11]
	v_cndmask_b32_e64 v65, v65, v71, s[10:11]
	v_cndmask_b32_e64 v64, v64, v70, s[10:11]
	s_waitcnt lgkmcnt(1)
	v_pk_add_f32 v[66:67], v[74:75], v[66:67]
	s_waitcnt lgkmcnt(0)
	v_pk_add_f32 v[64:65], v[64:65], v[76:77]
	v_and_b32_e32 v89, 0xffff0000, v212
	v_cndmask_b32_e64 v68, v66, v64, s[12:13]
	v_cndmask_b32_e64 v69, v67, v65, s[12:13]
	ds_bpermute_b32 v68, v206, v68
	ds_bpermute_b32 v69, v206, v69
	v_and_b32_e32 v91, 0xffff0000, v213
	v_lshlrev_b32_e32 v88, 16, v212
	v_lshlrev_b32_e32 v90, 16, v213
	v_readlane_b32 s98, v248, s59
	v_readlane_b32 s99, v249, s59
	v_cndmask_b32_e64 v65, v65, v67, s[12:13]
	v_cndmask_b32_e64 v64, v64, v66, s[12:13]
	v_pk_fma_f32 v[66:67], v[88:89], s[74:75], v[90:91] op_sel_hi:[1,0,1]
	v_lshlrev_b64 v[92:93], 13, v[186:187]
	v_pk_add_f32 v[66:67], v[66:67], s[98:99] op_sel_hi:[1,0] neg_lo:[0,1] neg_hi:[0,1]
	v_lshl_add_u64 v[70:71], s[78:79], 0, v[92:93]
	v_pk_mul_f32 v[66:67], s[98:99], v[66:67] op_sel:[1,0]
	s_waitcnt lgkmcnt(0)
	v_pk_add_f32 v[64:65], v[64:65], v[68:69]
	ds_bpermute_b32 v64, v250, v64
	ds_bpermute_b32 v65, v250, v65
	v_pk_fma_f32 v[66:67], v[66:67], v[178:179], v[180:181]
	v_lshl_add_u64 v[70:71], v[70:71], 0, v[138:139]
	s_waitcnt lgkmcnt(0)
	v_pk_fma_f32 v[64:65], v[66:67], s[74:75], v[64:65] op_sel_hi:[1,0,1]
	s_add_i32 s16, s16, 16
	s_addk_i32 s17, 0x100
	s_add_i32 s34, s34, 0x40000
	s_and_b64 vcc, exec, s[0:1]
	s_mov_b32 s0, s61
	global_store_dwordx2 v[70:71], v[64:65], off nt
	s_cbranch_vccnz .LBB0_938
.LBB0_934:
	s_add_i32 s15, s17, 0xffffff80
	s_and_b32 s15, s15, 0x780
	v_lshl_add_u32 v76, s15, 2, v189
	ds_read_b128 v[64:67], v76
	s_add_i32 s14, s34, 0xfffc0000
	s_add_i32 s1, s0, 1
	s_and_b32 s14, s14, 0x1e00000
	s_add_u32 s14, s38, s14
	s_waitcnt lgkmcnt(0)
	s_addc_u32 s15, s39, 0
	ds_read_b128 v[68:71], v76 offset:16
	ds_read_b128 v[72:75], v76 offset:32
	ds_read_b128 v[128:131], v76 offset:48
	v_lshl_or_b32 v65, v65, 7, v137
	v_lshl_or_b32 v64, v64, 7, v174
	global_load_dwordx4 v[124:127], v64, s[14:15]
	global_load_dwordx4 v[120:123], v65, s[14:15]
	v_lshl_or_b32 v64, v67, 7, v137
	v_lshl_or_b32 v65, v66, 7, v174
	global_load_dwordx4 v[116:119], v65, s[14:15]
	global_load_dwordx4 v[112:115], v64, s[14:15]
	s_waitcnt lgkmcnt(2)
	v_lshl_or_b32 v64, v69, 7, v137
	v_lshl_or_b32 v65, v68, 7, v174
	global_load_dwordx4 v[108:111], v65, s[14:15]
	global_load_dwordx4 v[104:107], v64, s[14:15]
	v_lshl_or_b32 v64, v71, 7, v137
	v_lshl_or_b32 v65, v70, 7, v174
	global_load_dwordx4 v[100:103], v65, s[14:15]
	global_load_dwordx4 v[96:99], v64, s[14:15]
	s_waitcnt lgkmcnt(1)
	v_lshl_or_b32 v64, v73, 7, v137
	v_lshl_or_b32 v65, v72, 7, v174
	global_load_dwordx4 v[92:95], v65, s[14:15]
	global_load_dwordx4 v[88:91], v64, s[14:15]
	s_and_b32 s59, s1, 15
	v_lshl_or_b32 v64, v75, 7, v137
	v_lshl_or_b32 v65, v74, 7, v174
	s_add_i32 s1, s16, -16
	v_or_b32_e32 v186, s59, v176
	global_load_dwordx4 v[84:87], v65, s[14:15]
	global_load_dwordx4 v[80:83], v64, s[14:15]
	s_waitcnt lgkmcnt(0)
	s_and_b32 s1, s1, 0x780
	v_ashrrev_i32_e32 v187, 31, v186
	v_lshl_or_b32 v64, v129, 7, v137
	v_lshl_or_b32 v65, v128, 7, v174
	v_or_b32_e32 v214, s1, v192
	global_load_dwordx4 v[76:79], v65, s[14:15]
	global_load_dwordx4 v[72:75], v64, s[14:15]
	v_lshlrev_b32_e32 v64, 7, v131
	v_lshlrev_b32_e32 v65, 7, v130
	v_or_b32_e32 v64, v64, v137
	v_or_b32_e32 v65, v65, v174
	s_and_b32 s1, s0, 14
	s_waitcnt vmcnt(30)
	v_cvt_pk_f32_fp8_e32 v[224:225], v0
	v_cvt_pk_f32_fp8_sdwa v[226:227], v0 src0_sel:WORD_1
	v_cvt_pk_f32_fp8_e32 v[228:229], v1
	v_cvt_pk_f32_fp8_sdwa v[230:231], v1 src0_sel:WORD_1
	global_load_dwordx4 v[68:71], v65, s[14:15]
	s_nop 0
	global_load_dwordx4 v[64:67], v64, s[14:15]
	v_lshl_add_u32 v128, s1, 9, v193
	s_waitcnt vmcnt(31)
	v_cvt_pk_f32_fp8_e32 v[240:241], v4
	v_cvt_pk_f32_fp8_sdwa v[242:243], v4 src0_sel:WORD_1
	v_cvt_pk_f32_fp8_e32 v[244:245], v5
	v_cvt_pk_f32_fp8_sdwa v[246:247], v5 src0_sel:WORD_1
	ds_read_b128 v[216:219], v128
	ds_read_b128 v[220:223], v128 offset:16
	ds_read_b128 v[132:135], v128 offset:32
	ds_read_b128 v[128:131], v128 offset:48
	v_cvt_pk_f32_fp8_e32 v[232:233], v2
	s_waitcnt lgkmcnt(3)
	v_pk_fma_f32 v[224:225], v[216:217], v[224:225], 0 op_sel_hi:[0,1,0]
	v_pk_fma_f32 v[226:227], v[216:217], v[226:227], 0 op_sel_hi:[0,1,0]
	v_pk_fma_f32 v[228:229], v[216:217], v[228:229], 0 op_sel_hi:[0,1,0]
	v_pk_fma_f32 v[230:231], v[216:217], v[230:231], 0 op_sel_hi:[0,1,0]
	v_cvt_pk_f32_fp8_sdwa v[234:235], v2 src0_sel:WORD_1
	v_cvt_pk_f32_fp8_e32 v[236:237], v3
	v_cvt_pk_f32_fp8_sdwa v[238:239], v3 src0_sel:WORD_1
	v_pk_fma_f32 v[224:225], v[216:217], v[240:241], v[224:225] op_sel:[1,0,0]
	v_pk_fma_f32 v[226:227], v[216:217], v[242:243], v[226:227] op_sel:[1,0,0]
	v_pk_fma_f32 v[228:229], v[216:217], v[244:245], v[228:229] op_sel:[1,0,0]
	v_pk_fma_f32 v[230:231], v[216:217], v[246:247], v[230:231] op_sel:[1,0,0]
	v_cvt_pk_f32_fp8_e32 v[240:241], v6
	v_cvt_pk_f32_fp8_sdwa v[242:243], v6 src0_sel:WORD_1
	v_cvt_pk_f32_fp8_e32 v[244:245], v7
	v_cvt_pk_f32_fp8_sdwa v[246:247], v7 src0_sel:WORD_1
	v_pk_fma_f32 v[232:233], v[216:217], v[232:233], 0 op_sel_hi:[0,1,0]
	v_pk_fma_f32 v[234:235], v[216:217], v[234:235], 0 op_sel_hi:[0,1,0]
	v_pk_fma_f32 v[236:237], v[216:217], v[236:237], 0 op_sel_hi:[0,1,0]
	v_pk_fma_f32 v[238:239], v[216:217], v[238:239], 0 op_sel_hi:[0,1,0]
	v_pk_fma_f32 v[232:233], v[216:217], v[240:241], v[232:233] op_sel:[1,0,0]
	v_pk_fma_f32 v[234:235], v[216:217], v[242:243], v[234:235] op_sel:[1,0,0]
	v_pk_fma_f32 v[236:237], v[216:217], v[244:245], v[236:237] op_sel:[1,0,0]
	v_pk_fma_f32 v[216:217], v[216:217], v[246:247], v[238:239] op_sel:[1,0,0]
	s_waitcnt vmcnt(30)
	v_cvt_pk_f32_fp8_e32 v[238:239], v8
	v_cvt_pk_f32_fp8_sdwa v[240:241], v8 src0_sel:WORD_1
	v_cvt_pk_f32_fp8_e32 v[242:243], v9
	v_cvt_pk_f32_fp8_sdwa v[244:245], v9 src0_sel:WORD_1
	v_pk_fma_f32 v[224:225], v[218:219], v[238:239], v[224:225] op_sel_hi:[0,1,1]
	v_pk_fma_f32 v[226:227], v[218:219], v[240:241], v[226:227] op_sel_hi:[0,1,1]
	v_pk_fma_f32 v[228:229], v[218:219], v[242:243], v[228:229] op_sel_hi:[0,1,1]
	v_pk_fma_f32 v[230:231], v[218:219], v[244:245], v[230:231] op_sel_hi:[0,1,1]
	v_cvt_pk_f32_fp8_e32 v[238:239], v10
	v_cvt_pk_f32_fp8_sdwa v[240:241], v10 src0_sel:WORD_1
	v_cvt_pk_f32_fp8_e32 v[242:243], v11
	v_cvt_pk_f32_fp8_sdwa v[244:245], v11 src0_sel:WORD_1
	v_pk_fma_f32 v[232:233], v[218:219], v[238:239], v[232:233] op_sel_hi:[0,1,1]
	v_pk_fma_f32 v[234:235], v[218:219], v[240:241], v[234:235] op_sel_hi:[0,1,1]
	v_pk_fma_f32 v[236:237], v[218:219], v[242:243], v[236:237] op_sel_hi:[0,1,1]
	v_pk_fma_f32 v[216:217], v[218:219], v[244:245], v[216:217] op_sel_hi:[0,1,1]
	v_mov_b32_e32 v138, v219
	s_waitcnt vmcnt(29)
	v_cvt_pk_f32_fp8_e32 v[218:219], v12
	v_cvt_pk_f32_fp8_sdwa v[238:239], v12 src0_sel:WORD_1
	v_cvt_pk_f32_fp8_e32 v[240:241], v13
	v_cvt_pk_f32_fp8_sdwa v[242:243], v13 src0_sel:WORD_1
	v_pk_fma_f32 v[218:219], v[138:139], v[218:219], v[224:225] op_sel_hi:[0,1,1]
	v_pk_fma_f32 v[224:225], v[138:139], v[238:239], v[226:227] op_sel_hi:[0,1,1]
	v_pk_fma_f32 v[226:227], v[138:139], v[240:241], v[228:229] op_sel_hi:[0,1,1]
	v_pk_fma_f32 v[228:229], v[138:139], v[242:243], v[230:231] op_sel_hi:[0,1,1]
	v_cvt_pk_f32_fp8_e32 v[230:231], v14
	v_cvt_pk_f32_fp8_sdwa v[238:239], v14 src0_sel:WORD_1
	v_cvt_pk_f32_fp8_e32 v[240:241], v15
	v_cvt_pk_f32_fp8_sdwa v[242:243], v15 src0_sel:WORD_1
	v_pk_fma_f32 v[230:231], v[138:139], v[230:231], v[232:233] op_sel_hi:[0,1,1]
	v_pk_fma_f32 v[232:233], v[138:139], v[238:239], v[234:235] op_sel_hi:[0,1,1]
	v_pk_fma_f32 v[234:235], v[138:139], v[240:241], v[236:237] op_sel_hi:[0,1,1]
	v_pk_fma_f32 v[216:217], v[138:139], v[242:243], v[216:217] op_sel_hi:[0,1,1]
	s_waitcnt vmcnt(28)
	v_cvt_pk_f32_fp8_e32 v[236:237], v16
	v_cvt_pk_f32_fp8_sdwa v[238:239], v16 src0_sel:WORD_1
	v_cvt_pk_f32_fp8_e32 v[240:241], v17
	v_cvt_pk_f32_fp8_sdwa v[242:243], v17 src0_sel:WORD_1
	s_waitcnt lgkmcnt(2)
	v_pk_fma_f32 v[218:219], v[220:221], v[236:237], v[218:219] op_sel_hi:[0,1,1]
	v_pk_fma_f32 v[224:225], v[220:221], v[238:239], v[224:225] op_sel_hi:[0,1,1]
	v_pk_fma_f32 v[226:227], v[220:221], v[240:241], v[226:227] op_sel_hi:[0,1,1]
	v_pk_fma_f32 v[228:229], v[220:221], v[242:243], v[228:229] op_sel_hi:[0,1,1]
	v_cvt_pk_f32_fp8_e32 v[236:237], v18
	v_cvt_pk_f32_fp8_sdwa v[238:239], v18 src0_sel:WORD_1
	v_cvt_pk_f32_fp8_e32 v[240:241], v19
	v_cvt_pk_f32_fp8_sdwa v[242:243], v19 src0_sel:WORD_1
	v_pk_fma_f32 v[230:231], v[220:221], v[236:237], v[230:231] op_sel_hi:[0,1,1]
	v_pk_fma_f32 v[232:233], v[220:221], v[238:239], v[232:233] op_sel_hi:[0,1,1]
	v_pk_fma_f32 v[234:235], v[220:221], v[240:241], v[234:235] op_sel_hi:[0,1,1]
	v_pk_fma_f32 v[216:217], v[220:221], v[242:243], v[216:217] op_sel_hi:[0,1,1]
	s_waitcnt vmcnt(27)
	v_cvt_pk_f32_fp8_e32 v[236:237], v20
	v_cvt_pk_f32_fp8_sdwa v[238:239], v20 src0_sel:WORD_1
	v_cvt_pk_f32_fp8_e32 v[240:241], v21
	v_cvt_pk_f32_fp8_sdwa v[242:243], v21 src0_sel:WORD_1
	v_pk_fma_f32 v[218:219], v[220:221], v[236:237], v[218:219] op_sel:[1,0,0]
	v_pk_fma_f32 v[224:225], v[220:221], v[238:239], v[224:225] op_sel:[1,0,0]
	v_pk_fma_f32 v[226:227], v[220:221], v[240:241], v[226:227] op_sel:[1,0,0]
	v_pk_fma_f32 v[228:229], v[220:221], v[242:243], v[228:229] op_sel:[1,0,0]
	v_cvt_pk_f32_fp8_e32 v[236:237], v22
	v_cvt_pk_f32_fp8_sdwa v[238:239], v22 src0_sel:WORD_1
	v_cvt_pk_f32_fp8_e32 v[240:241], v23
	v_cvt_pk_f32_fp8_sdwa v[242:243], v23 src0_sel:WORD_1
	v_pk_fma_f32 v[230:231], v[220:221], v[236:237], v[230:231] op_sel:[1,0,0]
	v_pk_fma_f32 v[232:233], v[220:221], v[238:239], v[232:233] op_sel:[1,0,0]
	v_pk_fma_f32 v[234:235], v[220:221], v[240:241], v[234:235] op_sel:[1,0,0]
	v_pk_fma_f32 v[216:217], v[220:221], v[242:243], v[216:217] op_sel:[1,0,0]
	s_waitcnt vmcnt(26)
	v_cvt_pk_f32_fp8_e32 v[220:221], v24
	v_cvt_pk_f32_fp8_sdwa v[236:237], v24 src0_sel:WORD_1
	v_cvt_pk_f32_fp8_e32 v[238:239], v25
	v_cvt_pk_f32_fp8_sdwa v[240:241], v25 src0_sel:WORD_1
	v_pk_fma_f32 v[218:219], v[222:223], v[220:221], v[218:219] op_sel_hi:[0,1,1]
	v_pk_fma_f32 v[220:221], v[222:223], v[236:237], v[224:225] op_sel_hi:[0,1,1]
	v_pk_fma_f32 v[224:225], v[222:223], v[238:239], v[226:227] op_sel_hi:[0,1,1]
	v_pk_fma_f32 v[226:227], v[222:223], v[240:241], v[228:229] op_sel_hi:[0,1,1]
	v_cvt_pk_f32_fp8_e32 v[228:229], v26
	v_cvt_pk_f32_fp8_sdwa v[236:237], v26 src0_sel:WORD_1
	v_cvt_pk_f32_fp8_e32 v[238:239], v27
	v_cvt_pk_f32_fp8_sdwa v[240:241], v27 src0_sel:WORD_1
	v_pk_fma_f32 v[228:229], v[222:223], v[228:229], v[230:231] op_sel_hi:[0,1,1]
	v_pk_fma_f32 v[230:231], v[222:223], v[236:237], v[232:233] op_sel_hi:[0,1,1]
	v_pk_fma_f32 v[232:233], v[222:223], v[238:239], v[234:235] op_sel_hi:[0,1,1]
	v_pk_fma_f32 v[216:217], v[222:223], v[240:241], v[216:217] op_sel_hi:[0,1,1]
	v_mov_b32_e32 v138, v223
	s_waitcnt vmcnt(25)
	v_cvt_pk_f32_fp8_e32 v[222:223], v28
	v_cvt_pk_f32_fp8_sdwa v[234:235], v28 src0_sel:WORD_1
	v_cvt_pk_f32_fp8_e32 v[236:237], v29
	v_cvt_pk_f32_fp8_sdwa v[238:239], v29 src0_sel:WORD_1
	v_pk_fma_f32 v[218:219], v[138:139], v[222:223], v[218:219] op_sel_hi:[0,1,1]
	v_pk_fma_f32 v[220:221], v[138:139], v[234:235], v[220:221] op_sel_hi:[0,1,1]
	v_pk_fma_f32 v[222:223], v[138:139], v[236:237], v[224:225] op_sel_hi:[0,1,1]
	v_pk_fma_f32 v[224:225], v[138:139], v[238:239], v[226:227] op_sel_hi:[0,1,1]
	v_cvt_pk_f32_fp8_e32 v[226:227], v30
	v_cvt_pk_f32_fp8_sdwa v[234:235], v30 src0_sel:WORD_1
	v_cvt_pk_f32_fp8_e32 v[236:237], v31
	v_cvt_pk_f32_fp8_sdwa v[238:239], v31 src0_sel:WORD_1
	v_pk_fma_f32 v[226:227], v[138:139], v[226:227], v[228:229] op_sel_hi:[0,1,1]
	v_pk_fma_f32 v[228:229], v[138:139], v[234:235], v[230:231] op_sel_hi:[0,1,1]
	v_pk_fma_f32 v[230:231], v[138:139], v[236:237], v[232:233] op_sel_hi:[0,1,1]
	v_pk_fma_f32 v[216:217], v[138:139], v[238:239], v[216:217] op_sel_hi:[0,1,1]
	s_waitcnt vmcnt(24)
	v_cvt_pk_f32_fp8_e32 v[232:233], v32
	v_cvt_pk_f32_fp8_sdwa v[234:235], v32 src0_sel:WORD_1
	v_cvt_pk_f32_fp8_e32 v[236:237], v33
	v_cvt_pk_f32_fp8_sdwa v[238:239], v33 src0_sel:WORD_1
	s_waitcnt lgkmcnt(1)
	v_pk_fma_f32 v[218:219], v[132:133], v[232:233], v[218:219] op_sel_hi:[0,1,1]
	v_pk_fma_f32 v[220:221], v[132:133], v[234:235], v[220:221] op_sel_hi:[0,1,1]
	v_pk_fma_f32 v[222:223], v[132:133], v[236:237], v[222:223] op_sel_hi:[0,1,1]
	v_pk_fma_f32 v[224:225], v[132:133], v[238:239], v[224:225] op_sel_hi:[0,1,1]
	v_cvt_pk_f32_fp8_e32 v[232:233], v34
	v_cvt_pk_f32_fp8_sdwa v[234:235], v34 src0_sel:WORD_1
	v_cvt_pk_f32_fp8_e32 v[236:237], v35
	v_cvt_pk_f32_fp8_sdwa v[238:239], v35 src0_sel:WORD_1
	v_pk_fma_f32 v[226:227], v[132:133], v[232:233], v[226:227] op_sel_hi:[0,1,1]
	v_pk_fma_f32 v[228:229], v[132:133], v[234:235], v[228:229] op_sel_hi:[0,1,1]
	v_pk_fma_f32 v[230:231], v[132:133], v[236:237], v[230:231] op_sel_hi:[0,1,1]
	v_pk_fma_f32 v[216:217], v[132:133], v[238:239], v[216:217] op_sel_hi:[0,1,1]
	s_waitcnt vmcnt(23)
	v_cvt_pk_f32_fp8_e32 v[232:233], v36
	v_cvt_pk_f32_fp8_sdwa v[234:235], v36 src0_sel:WORD_1
	v_cvt_pk_f32_fp8_e32 v[236:237], v37
	v_cvt_pk_f32_fp8_sdwa v[238:239], v37 src0_sel:WORD_1
	v_pk_fma_f32 v[218:219], v[132:133], v[232:233], v[218:219] op_sel:[1,0,0]
	v_pk_fma_f32 v[220:221], v[132:133], v[234:235], v[220:221] op_sel:[1,0,0]
	v_pk_fma_f32 v[222:223], v[132:133], v[236:237], v[222:223] op_sel:[1,0,0]
	v_pk_fma_f32 v[224:225], v[132:133], v[238:239], v[224:225] op_sel:[1,0,0]
	v_cvt_pk_f32_fp8_e32 v[232:233], v38
	v_cvt_pk_f32_fp8_sdwa v[234:235], v38 src0_sel:WORD_1
	v_cvt_pk_f32_fp8_e32 v[236:237], v39
	v_cvt_pk_f32_fp8_sdwa v[238:239], v39 src0_sel:WORD_1
	v_pk_fma_f32 v[226:227], v[132:133], v[232:233], v[226:227] op_sel:[1,0,0]
	v_pk_fma_f32 v[228:229], v[132:133], v[234:235], v[228:229] op_sel:[1,0,0]
	v_pk_fma_f32 v[230:231], v[132:133], v[236:237], v[230:231] op_sel:[1,0,0]
	v_pk_fma_f32 v[132:133], v[132:133], v[238:239], v[216:217] op_sel:[1,0,0]
	s_waitcnt vmcnt(22)
	v_cvt_pk_f32_fp8_e32 v[216:217], v40
	v_cvt_pk_f32_fp8_sdwa v[232:233], v40 src0_sel:WORD_1
	v_cvt_pk_f32_fp8_e32 v[234:235], v41
	v_cvt_pk_f32_fp8_sdwa v[236:237], v41 src0_sel:WORD_1
	v_pk_fma_f32 v[216:217], v[134:135], v[216:217], v[218:219] op_sel_hi:[0,1,1]
	v_pk_fma_f32 v[218:219], v[134:135], v[232:233], v[220:221] op_sel_hi:[0,1,1]
	v_pk_fma_f32 v[220:221], v[134:135], v[234:235], v[222:223] op_sel_hi:[0,1,1]
	v_pk_fma_f32 v[222:223], v[134:135], v[236:237], v[224:225] op_sel_hi:[0,1,1]
	v_cvt_pk_f32_fp8_e32 v[224:225], v42
	v_cvt_pk_f32_fp8_sdwa v[232:233], v42 src0_sel:WORD_1
	v_cvt_pk_f32_fp8_e32 v[234:235], v43
	v_cvt_pk_f32_fp8_sdwa v[236:237], v43 src0_sel:WORD_1
	v_pk_fma_f32 v[224:225], v[134:135], v[224:225], v[226:227] op_sel_hi:[0,1,1]
	v_pk_fma_f32 v[226:227], v[134:135], v[232:233], v[228:229] op_sel_hi:[0,1,1]
	v_pk_fma_f32 v[228:229], v[134:135], v[234:235], v[230:231] op_sel_hi:[0,1,1]
	v_pk_fma_f32 v[132:133], v[134:135], v[236:237], v[132:133] op_sel_hi:[0,1,1]
	s_waitcnt vmcnt(21)
	v_cvt_pk_f32_fp8_e32 v[230:231], v44
	v_cvt_pk_f32_fp8_sdwa v[232:233], v44 src0_sel:WORD_1
	v_cvt_pk_f32_fp8_e32 v[234:235], v45
	v_cvt_pk_f32_fp8_sdwa v[236:237], v45 src0_sel:WORD_1
	v_mov_b32_e32 v134, v135
	v_pk_fma_f32 v[216:217], v[134:135], v[230:231], v[216:217] op_sel_hi:[0,1,1]
	v_pk_fma_f32 v[218:219], v[134:135], v[232:233], v[218:219] op_sel_hi:[0,1,1]
	v_pk_fma_f32 v[220:221], v[134:135], v[234:235], v[220:221] op_sel_hi:[0,1,1]
	v_pk_fma_f32 v[222:223], v[134:135], v[236:237], v[222:223] op_sel_hi:[0,1,1]
	v_cvt_pk_f32_fp8_e32 v[230:231], v46
	v_cvt_pk_f32_fp8_sdwa v[232:233], v46 src0_sel:WORD_1
	v_cvt_pk_f32_fp8_e32 v[234:235], v47
	v_cvt_pk_f32_fp8_sdwa v[236:237], v47 src0_sel:WORD_1
	v_pk_fma_f32 v[224:225], v[134:135], v[230:231], v[224:225] op_sel_hi:[0,1,1]
	v_pk_fma_f32 v[226:227], v[134:135], v[232:233], v[226:227] op_sel_hi:[0,1,1]
	v_pk_fma_f32 v[228:229], v[134:135], v[234:235], v[228:229] op_sel_hi:[0,1,1]
	v_pk_fma_f32 v[132:133], v[134:135], v[236:237], v[132:133] op_sel_hi:[0,1,1]
	s_waitcnt vmcnt(20)
	v_cvt_pk_f32_fp8_e32 v[134:135], v48
	v_cvt_pk_f32_fp8_sdwa v[230:231], v48 src0_sel:WORD_1
	v_cvt_pk_f32_fp8_e32 v[232:233], v49
	v_cvt_pk_f32_fp8_sdwa v[234:235], v49 src0_sel:WORD_1
	s_waitcnt lgkmcnt(0)
	v_pk_fma_f32 v[134:135], v[128:129], v[134:135], v[216:217] op_sel_hi:[0,1,1]
	v_pk_fma_f32 v[216:217], v[128:129], v[230:231], v[218:219] op_sel_hi:[0,1,1]
	v_pk_fma_f32 v[218:219], v[128:129], v[232:233], v[220:221] op_sel_hi:[0,1,1]
	v_pk_fma_f32 v[220:221], v[128:129], v[234:235], v[222:223] op_sel_hi:[0,1,1]
	v_cvt_pk_f32_fp8_e32 v[222:223], v50
	v_cvt_pk_f32_fp8_sdwa v[230:231], v50 src0_sel:WORD_1
	v_cvt_pk_f32_fp8_e32 v[232:233], v51
	v_cvt_pk_f32_fp8_sdwa v[234:235], v51 src0_sel:WORD_1
	v_pk_fma_f32 v[222:223], v[128:129], v[222:223], v[224:225] op_sel_hi:[0,1,1]
	v_pk_fma_f32 v[224:225], v[128:129], v[230:231], v[226:227] op_sel_hi:[0,1,1]
	v_pk_fma_f32 v[226:227], v[128:129], v[232:233], v[228:229] op_sel_hi:[0,1,1]
	v_pk_fma_f32 v[132:133], v[128:129], v[234:235], v[132:133] op_sel_hi:[0,1,1]
	s_waitcnt vmcnt(19)
	v_cvt_pk_f32_fp8_e32 v[228:229], v52
	v_cvt_pk_f32_fp8_sdwa v[230:231], v52 src0_sel:WORD_1
	v_cvt_pk_f32_fp8_e32 v[232:233], v53
	v_cvt_pk_f32_fp8_sdwa v[234:235], v53 src0_sel:WORD_1
	v_pk_fma_f32 v[134:135], v[128:129], v[228:229], v[134:135] op_sel:[1,0,0]
	v_pk_fma_f32 v[216:217], v[128:129], v[230:231], v[216:217] op_sel:[1,0,0]
	v_pk_fma_f32 v[218:219], v[128:129], v[232:233], v[218:219] op_sel:[1,0,0]
	v_pk_fma_f32 v[220:221], v[128:129], v[234:235], v[220:221] op_sel:[1,0,0]
	v_cvt_pk_f32_fp8_e32 v[228:229], v54
	v_cvt_pk_f32_fp8_sdwa v[230:231], v54 src0_sel:WORD_1
	v_cvt_pk_f32_fp8_e32 v[232:233], v55
	v_cvt_pk_f32_fp8_sdwa v[234:235], v55 src0_sel:WORD_1
	v_pk_fma_f32 v[222:223], v[128:129], v[228:229], v[222:223] op_sel:[1,0,0]
	v_pk_fma_f32 v[224:225], v[128:129], v[230:231], v[224:225] op_sel:[1,0,0]
	v_pk_fma_f32 v[226:227], v[128:129], v[232:233], v[226:227] op_sel:[1,0,0]
	v_pk_fma_f32 v[128:129], v[128:129], v[234:235], v[132:133] op_sel:[1,0,0]
	s_waitcnt vmcnt(18)
	v_cvt_pk_f32_fp8_e32 v[132:133], v56
	v_cvt_pk_f32_fp8_sdwa v[228:229], v56 src0_sel:WORD_1
	v_cvt_pk_f32_fp8_e32 v[230:231], v57
	v_cvt_pk_f32_fp8_sdwa v[232:233], v57 src0_sel:WORD_1
	v_pk_fma_f32 v[132:133], v[130:131], v[132:133], v[134:135] op_sel_hi:[0,1,1]
	v_pk_fma_f32 v[134:135], v[130:131], v[228:229], v[216:217] op_sel_hi:[0,1,1]
	v_pk_fma_f32 v[216:217], v[130:131], v[230:231], v[218:219] op_sel_hi:[0,1,1]
	v_pk_fma_f32 v[218:219], v[130:131], v[232:233], v[220:221] op_sel_hi:[0,1,1]
	v_cvt_pk_f32_fp8_e32 v[220:221], v58
	v_cvt_pk_f32_fp8_sdwa v[228:229], v58 src0_sel:WORD_1
	v_cvt_pk_f32_fp8_e32 v[230:231], v59
	v_cvt_pk_f32_fp8_sdwa v[232:233], v59 src0_sel:WORD_1
	v_pk_fma_f32 v[220:221], v[130:131], v[220:221], v[222:223] op_sel_hi:[0,1,1]
	v_pk_fma_f32 v[222:223], v[130:131], v[228:229], v[224:225] op_sel_hi:[0,1,1]
	s_waitcnt vmcnt(17)
	s_and_b32 s101, s1, 3
	v_lshl_add_u32 v253, s101, 8, v252
	ds_read_b32 v210, v253
	ds_read_b32 v211, v253 offset:1024
	v_cvt_pk_f32_fp8_sdwa v[228:229], v60 src0_sel:WORD_1
	v_pk_fma_f32 v[224:225], v[130:131], v[230:231], v[226:227] op_sel_hi:[0,1,1]
	v_cvt_pk_f32_fp8_e32 v[226:227], v60
	v_cvt_pk_f32_fp8_e32 v[230:231], v61
	v_pk_fma_f32 v[128:129], v[130:131], v[232:233], v[128:129] op_sel_hi:[0,1,1]
	v_mov_b32_e32 v130, v131
	v_cvt_pk_f32_fp8_sdwa v[232:233], v61 src0_sel:WORD_1
	v_pk_fma_f32 v[134:135], v[130:131], v[228:229], v[134:135] op_sel_hi:[0,1,1]
	v_cvt_pk_f32_fp8_sdwa v[228:229], v62 src0_sel:WORD_1
	v_pk_fma_f32 v[132:133], v[130:131], v[226:227], v[132:133] op_sel_hi:[0,1,1]
	v_pk_fma_f32 v[216:217], v[130:131], v[230:231], v[216:217] op_sel_hi:[0,1,1]
	v_cvt_pk_f32_fp8_e32 v[226:227], v62
	v_cvt_pk_f32_fp8_e32 v[230:231], v63
	v_pk_fma_f32 v[218:219], v[130:131], v[232:233], v[218:219] op_sel_hi:[0,1,1]
	v_cvt_pk_f32_fp8_sdwa v[232:233], v63 src0_sel:WORD_1
	v_pk_fma_f32 v[222:223], v[130:131], v[228:229], v[222:223] op_sel_hi:[0,1,1]
	v_cndmask_b32_e64 v138, v134, v222, s[8:9]
	v_pk_fma_f32 v[220:221], v[130:131], v[226:227], v[220:221] op_sel_hi:[0,1,1]
	v_pk_fma_f32 v[224:225], v[130:131], v[230:231], v[224:225] op_sel_hi:[0,1,1]
	ds_bpermute_b32 v226, v204, v138
	v_cndmask_b32_e64 v138, v135, v223, s[8:9]
	ds_bpermute_b32 v227, v204, v138
	v_cndmask_b32_e64 v138, v216, v224, s[8:9]
	v_pk_fma_f32 v[128:129], v[130:131], v[232:233], v[128:129] op_sel_hi:[0,1,1]
	v_cndmask_b32_e64 v130, v132, v220, s[8:9]
	v_cndmask_b32_e64 v131, v133, v221, s[8:9]
	ds_bpermute_b32 v228, v204, v138
	v_cndmask_b32_e64 v138, v217, v225, s[8:9]
	ds_bpermute_b32 v130, v204, v130
	ds_bpermute_b32 v131, v204, v131
	ds_bpermute_b32 v229, v204, v138
	v_cndmask_b32_e64 v138, v218, v128, s[8:9]
	ds_bpermute_b32 v230, v204, v138
	v_cndmask_b32_e64 v138, v219, v129, s[8:9]
	ds_bpermute_b32 v231, v204, v138
	v_cndmask_b32_e64 v133, v221, v133, s[8:9]
	v_cndmask_b32_e64 v132, v220, v132, s[8:9]
	s_waitcnt lgkmcnt(3)
	v_pk_add_f32 v[130:131], v[132:133], v[130:131]
	v_cndmask_b32_e64 v133, v223, v135, s[8:9]
	v_cndmask_b32_e64 v132, v222, v134, s[8:9]
	v_cndmask_b32_e64 v135, v225, v217, s[8:9]
	v_cndmask_b32_e64 v134, v224, v216, s[8:9]
	s_waitcnt lgkmcnt(2)
	v_pk_add_f32 v[134:135], v[134:135], v[228:229]
	v_cndmask_b32_e64 v129, v129, v219, s[8:9]
	v_cndmask_b32_e64 v128, v128, v218, s[8:9]
	v_pk_add_f32 v[132:133], v[132:133], v[226:227]
	s_waitcnt lgkmcnt(0)
	v_pk_add_f32 v[128:129], v[128:129], v[230:231]
	v_cndmask_b32_e64 v219, v135, v131, s[10:11]
	v_cndmask_b32_e64 v131, v131, v135, s[10:11]
	ds_bpermute_b32 v217, v205, v131
	v_cndmask_b32_e64 v131, v132, v128, s[10:11]
	v_cndmask_b32_e64 v138, v130, v134, s[10:11]
	ds_bpermute_b32 v220, v205, v131
	v_cndmask_b32_e64 v131, v133, v129, s[10:11]
	ds_bpermute_b32 v216, v205, v138
	ds_bpermute_b32 v221, v205, v131
	v_cndmask_b32_e64 v218, v134, v130, s[10:11]
	v_cndmask_b32_e64 v129, v129, v133, s[10:11]
	v_cndmask_b32_e64 v128, v128, v132, s[10:11]
	s_waitcnt lgkmcnt(1)
	v_pk_add_f32 v[130:131], v[218:219], v[216:217]
	s_waitcnt lgkmcnt(0)
	v_pk_add_f32 v[132:133], v[128:129], v[220:221]
	s_cmp_lg_u32 s1, 0
	v_cndmask_b32_e64 v128, v130, v132, s[12:13]
	v_cndmask_b32_e64 v129, v131, v133, s[12:13]
	ds_bpermute_b32 v128, v206, v128
	ds_bpermute_b32 v129, v206, v129
	v_lshlrev_b32_e32 v138, 2, v214
	s_cbranch_scc1 .LBB0_936
	global_load_dwordx2 v[178:179], v138, s[46:47]
	global_load_dwordx2 v[180:181], v138, s[48:49]
.LBB0_936:
	v_cndmask_b32_e64 v131, v133, v131, s[12:13]
	v_cndmask_b32_e64 v130, v132, v130, s[12:13]
	s_waitcnt lgkmcnt(2)
	v_lshlrev_b32_e32 v132, 16, v210
	v_and_b32_e32 v133, 0xffff0000, v210
	v_lshlrev_b32_e32 v134, 16, v211
	v_and_b32_e32 v135, 0xffff0000, v211
	v_readlane_b32 s98, v248, s1
	v_readlane_b32 s99, v249, s1
	v_or_b32_e32 v214, s1, v176
	s_waitcnt lgkmcnt(0)
	v_pk_add_f32 v[128:129], v[130:131], v[128:129]
	ds_bpermute_b32 v128, v250, v128
	ds_bpermute_b32 v129, v250, v129
	v_pk_fma_f32 v[130:131], v[132:133], s[74:75], v[134:135] op_sel_hi:[1,0,1]
	v_ashrrev_i32_e32 v215, 31, v214
	v_pk_add_f32 v[130:131], v[130:131], s[98:99] op_sel_hi:[1,0] neg_lo:[0,1] neg_hi:[0,1]
	s_add_i32 s61, s0, 2
	v_lshlrev_b64 v[214:215], 13, v[214:215]
	v_pk_mul_f32 v[130:131], s[98:99], v[130:131] op_sel:[1,0]
	s_cmpk_gt_u32 s0, 0xfd
	v_lshl_add_u64 v[214:215], s[78:79], 0, v[214:215]
	s_waitcnt vmcnt(0)
	v_pk_fma_f32 v[130:131], v[130:131], v[178:179], v[180:181]
	s_cselect_b64 s[0:1], -1, 0
	v_lshl_add_u64 v[214:215], v[214:215], 0, v[138:139]
	s_waitcnt lgkmcnt(0)
	v_pk_fma_f32 v[128:129], v[130:131], s[74:75], v[128:129] op_sel_hi:[1,0,1]
	s_and_b64 vcc, exec, s[0:1]
	global_store_dwordx2 v[214:215], v[128:129], off nt
	s_cbranch_vccnz .LBB0_933
	s_and_b32 s15, s17, 0x700
	v_lshl_add_u32 v0, s15, 2, v189
	ds_read_b128 v[6:9], v0
	ds_read_b128 v[22:25], v0 offset:16
	ds_read_b128 v[38:41], v0 offset:32
	ds_read_b128 v[54:57], v0 offset:48
	s_and_b32 s14, s34, 0x3e00000
	s_add_u32 s14, s38, s14
	s_waitcnt lgkmcnt(2)
	s_waitcnt lgkmcnt(1)
	s_waitcnt lgkmcnt(0)
	s_addc_u32 s15, s39, 0
	v_lshl_or_b32 v4, v7, 7, v137
	v_lshl_or_b32 v0, v6, 7, v174
	v_lshl_or_b32 v12, v9, 7, v137
	v_lshl_or_b32 v8, v8, 7, v174
	v_lshl_or_b32 v20, v23, 7, v137
	v_lshl_or_b32 v16, v22, 7, v174
	v_lshl_or_b32 v28, v25, 7, v137
	v_lshl_or_b32 v24, v24, 7, v174
	v_lshl_or_b32 v36, v39, 7, v137
	v_lshl_or_b32 v32, v38, 7, v174
	v_lshl_or_b32 v44, v41, 7, v137
	v_lshl_or_b32 v40, v40, 7, v174
	v_lshl_or_b32 v52, v55, 7, v137
	v_lshl_or_b32 v48, v54, 7, v174
	v_lshl_or_b32 v60, v57, 7, v137
	v_lshl_or_b32 v56, v56, 7, v174
	global_load_dwordx4 v[0:3], v0, s[14:15]
	s_nop 0
	global_load_dwordx4 v[4:7], v4, s[14:15]
	s_nop 0
	global_load_dwordx4 v[8:11], v8, s[14:15]
	s_nop 0
	global_load_dwordx4 v[12:15], v12, s[14:15]
	s_nop 0
	global_load_dwordx4 v[16:19], v16, s[14:15]
	s_nop 0
	global_load_dwordx4 v[20:23], v20, s[14:15]
	s_nop 0
	global_load_dwordx4 v[24:27], v24, s[14:15]
	s_nop 0
	global_load_dwordx4 v[28:31], v28, s[14:15]
	s_nop 0
	global_load_dwordx4 v[32:35], v32, s[14:15]
	s_nop 0
	global_load_dwordx4 v[36:39], v36, s[14:15]
	s_nop 0
	global_load_dwordx4 v[40:43], v40, s[14:15]
	s_nop 0
	global_load_dwordx4 v[44:47], v44, s[14:15]
	s_nop 0
	global_load_dwordx4 v[48:51], v48, s[14:15]
	s_nop 0
	global_load_dwordx4 v[52:55], v52, s[14:15]
	s_nop 0
	global_load_dwordx4 v[56:59], v56, s[14:15]
	s_nop 0
	global_load_dwordx4 v[60:63], v60, s[14:15]
	s_branch .LBB0_933

	.amdhsa_kernel _Z4mega6Paramsii
		.amdhsa_group_segment_fixed_size 16400
		.amdhsa_private_segment_fixed_size 0
		.amdhsa_kernarg_size 416
		.amdhsa_user_sgpr_count 2
		.amdhsa_user_sgpr_dispatch_ptr 0
		.amdhsa_user_sgpr_queue_ptr 0
		.amdhsa_user_sgpr_kernarg_segment_ptr 1
		.amdhsa_user_sgpr_dispatch_id 0
		.amdhsa_user_sgpr_kernarg_preload_length 0
		.amdhsa_user_sgpr_kernarg_preload_offset 0
		.amdhsa_user_sgpr_private_segment_size 0
		.amdhsa_uses_dynamic_stack 0
		.amdhsa_enable_private_segment 0
		.amdhsa_system_sgpr_workgroup_id_x 1
		.amdhsa_system_sgpr_workgroup_id_y 0
		.amdhsa_system_sgpr_workgroup_id_z 0
		.amdhsa_system_sgpr_workgroup_info 0
		.amdhsa_system_vgpr_workitem_id 2
		.amdhsa_next_free_vgpr 256
		.amdhsa_next_free_sgpr 102
		.amdhsa_accum_offset 256
		.amdhsa_reserve_vcc 1
		.amdhsa_float_round_mode_32 0
		.amdhsa_float_round_mode_16_64 0
		.amdhsa_float_denorm_mode_32 3
		.amdhsa_float_denorm_mode_16_64 3
		.amdhsa_dx10_clamp 1
		.amdhsa_ieee_mode 1
		.amdhsa_fp16_overflow 0
		.amdhsa_tg_split 0
		.amdhsa_exception_fp_ieee_invalid_op 0
		.amdhsa_exception_fp_denorm_src 0
		.amdhsa_exception_fp_ieee_div_zero 0
		.amdhsa_exception_fp_ieee_overflow 0
		.amdhsa_exception_fp_ieee_underflow 0
		.amdhsa_exception_fp_ieee_inexact 0
		.amdhsa_exception_int_div_zero 0
	.end_amdhsa_kernel

amdhsa.kernels:
  - .agpr_count:     0
    .args:
      - .offset:         0
        .size:           152
        .value_kind:     by_value
      - .offset:         152
        .size:           4
        .value_kind:     by_value
      - .offset:         156
        .size:           4
        .value_kind:     by_value
      - .offset:         160
        .size:           4
        .value_kind:     hidden_block_count_x
      - .offset:         164
        .size:           4
        .value_kind:     hidden_block_count_y
      - .offset:         168
        .size:           4
        .value_kind:     hidden_block_count_z
      - .offset:         172
        .size:           2
        .value_kind:     hidden_group_size_x
      - .offset:         174
        .size:           2
        .value_kind:     hidden_group_size_y
      - .offset:         176
        .size:           2
        .value_kind:     hidden_group_size_z
      - .offset:         178
        .size:           2
        .value_kind:     hidden_remainder_x
      - .offset:         180
        .size:           2
        .value_kind:     hidden_remainder_y
      - .offset:         182
        .size:           2
        .value_kind:     hidden_remainder_z
      - .offset:         200
        .size:           8
        .value_kind:     hidden_global_offset_x
      - .offset:         208
        .size:           8
        .value_kind:     hidden_global_offset_y
      - .offset:         216
        .size:           8
        .value_kind:     hidden_global_offset_z
      - .offset:         224
        .size:           2
        .value_kind:     hidden_grid_dims
      - .offset:         248
        .size:           8
        .value_kind:     hidden_multigrid_sync_arg
      - .offset:         280
        .size:           4
        .value_kind:     hidden_dynamic_lds_size
    .group_segment_fixed_size: 16400
    .kernarg_segment_align: 8
    .kernarg_segment_size: 416
    .language:       OpenCL C
    .language_version:
      - 2
      - 0
    .max_flat_workgroup_size: 512
    .name:           _Z4mega6Paramsii
    .private_segment_fixed_size: 0
    .sgpr_count:     108
    .sgpr_spill_count: 13
    .symbol:         _Z4mega6Paramsii.kd
    .uniform_work_group_size: 1
    .uses_dynamic_stack: false
    .vgpr_count:     256
    .vgpr_spill_count: 0
    .wavefront_size: 64
